# epi
# speedup vs baseline: 1.0025x; 1.0025x over previous
; __device__ void phase_attn(const Params& p, char* smem) {
;     ...
;       for (int m = 0; m < 2; ++m)
; #pragma unroll
;         for (int nn = 0; nn < 4; ++nn)
; #pragma unroll
;           for (int j = 0; j < 4; ++j) rowss[m][j] += Oc[m][nn][j] * Oc[m][nn][j];
; #pragma unroll
;       for (int m = 0; m < 2; ++m)
; #pragma unroll
;         for (int nn = 0; nn < 4; ++nn) {
;           if (hh == 0) {
; #pragma unroll
;             for (int j = 0; j < 4; ++j) sO[((m * 4 + nn) * 4 + j) * 64 + lane] = Oc[m][nn][j];
;           } else {
;             O1[m][nn] = Oc[m][nn];
;           }
;         }
;     }
; #pragma unroll
;     for (int m = 0; m < 2; ++m)
; #pragma unroll
;       for (int j = 0; j < 4; ++j) {
;         const float v = row16_sum(rowss[m][j]);
;         if (l15 == 0) sSsq[w * 32 + m * 16 + lq * 4 + j] = v;
;       }
.LBB0_235:
	v_mul_f32_e32 v20, v20, v20
	v_fmac_f32_e32 v20, v16, v16
	v_fmac_f32_e32 v20, v24, v24
	v_fmac_f32_e32 v20, v28, v28
	v_fmac_f32_e32 v20, v48, v48
	v_fmac_f32_e32 v20, v52, v52
	v_fmac_f32_e32 v20, v56, v56
	v_fmac_f32_e32 v20, v60, v60
	s_nop 1
	v_add_f32_dpp v16, v20, v20 quad_perm:[1,0,3,2] row_mask:0xf bank_mask:0xf bound_ctrl:1
	s_nop 1
	v_add_f32_dpp v16, v16, v16 quad_perm:[2,3,0,1] row_mask:0xf bank_mask:0xf bound_ctrl:1
	s_nop 1
	v_add_f32_dpp v20, v16, v16 row_half_mirror row_mask:0xf bank_mask:0xf bound_ctrl:1
	v_add_u32_e32 v16, v128, v130
	s_nop 0
	v_mov_b32_dpp v24, v20 row_ror:8 row_mask:0xf bank_mask:0xf bound_ctrl:1
	s_and_saveexec_b64 s[6:7], s[4:5]
	v_add_f32_e32 v20, v20, v24
	ds_write_b32 v16, v20 offset:18432
	s_or_b64 exec, exec, s[6:7]
	v_mul_f32_e32 v20, v21, v21
	v_fmac_f32_e32 v20, v17, v17
	v_fmac_f32_e32 v20, v25, v25
	v_fmac_f32_e32 v20, v29, v29
	v_fmac_f32_e32 v20, v49, v49
	v_fmac_f32_e32 v20, v53, v53
	v_fmac_f32_e32 v20, v57, v57
	v_fmac_f32_e32 v20, v61, v61
	s_nop 1
	v_add_f32_dpp v17, v20, v20 quad_perm:[1,0,3,2] row_mask:0xf bank_mask:0xf bound_ctrl:1
	s_nop 1
	v_add_f32_dpp v17, v17, v17 quad_perm:[2,3,0,1] row_mask:0xf bank_mask:0xf bound_ctrl:1
	s_nop 1
	v_add_f32_dpp v17, v17, v17 row_half_mirror row_mask:0xf bank_mask:0xf bound_ctrl:1
	s_nop 1
	v_mov_b32_dpp v20, v17 row_ror:8 row_mask:0xf bank_mask:0xf bound_ctrl:1
	s_and_saveexec_b64 s[6:7], s[4:5]
	v_add_f32_e32 v17, v17, v20
	ds_write_b32 v16, v17 offset:18436
	s_or_b64 exec, exec, s[6:7]
	v_mul_f32_e32 v17, v22, v22
	v_fmac_f32_e32 v17, v18, v18
	v_fmac_f32_e32 v17, v26, v26
	v_fmac_f32_e32 v17, v30, v30
	v_fmac_f32_e32 v17, v50, v50
	v_fmac_f32_e32 v17, v54, v54
	v_fmac_f32_e32 v17, v58, v58
	v_fmac_f32_e32 v17, v62, v62
	s_nop 1
	v_add_f32_dpp v17, v17, v17 quad_perm:[1,0,3,2] row_mask:0xf bank_mask:0xf bound_ctrl:1
	s_nop 1
	v_add_f32_dpp v17, v17, v17 quad_perm:[2,3,0,1] row_mask:0xf bank_mask:0xf bound_ctrl:1
	s_nop 1
	v_add_f32_dpp v17, v17, v17 row_half_mirror row_mask:0xf bank_mask:0xf bound_ctrl:1
	s_nop 1
	v_mov_b32_dpp v18, v17 row_ror:8 row_mask:0xf bank_mask:0xf bound_ctrl:1
	s_and_saveexec_b64 s[6:7], s[4:5]
	v_add_f32_e32 v17, v17, v18
	ds_write_b32 v16, v17 offset:18440
	s_or_b64 exec, exec, s[6:7]
	v_mul_f32_e32 v17, v23, v23
	v_fmac_f32_e32 v17, v19, v19
	v_fmac_f32_e32 v17, v27, v27
	v_fmac_f32_e32 v17, v31, v31
	v_fmac_f32_e32 v17, v51, v51
	v_fmac_f32_e32 v17, v55, v55
	v_fmac_f32_e32 v17, v59, v59
	v_fmac_f32_e32 v17, v63, v63
	s_nop 1
	v_add_f32_dpp v17, v17, v17 quad_perm:[1,0,3,2] row_mask:0xf bank_mask:0xf bound_ctrl:1
	s_nop 1
	v_add_f32_dpp v17, v17, v17 quad_perm:[2,3,0,1] row_mask:0xf bank_mask:0xf bound_ctrl:1
	s_nop 1
	v_add_f32_dpp v17, v17, v17 row_half_mirror row_mask:0xf bank_mask:0xf bound_ctrl:1
	s_nop 1
	v_mov_b32_dpp v18, v17 row_ror:8 row_mask:0xf bank_mask:0xf bound_ctrl:1
	s_and_saveexec_b64 s[6:7], s[4:5]
	v_add_f32_e32 v17, v17, v18
	ds_write_b32 v16, v17 offset:18444
	s_or_b64 exec, exec, s[6:7]
	v_mul_f32_e32 v4, v4, v4
	v_fmac_f32_e32 v4, v0, v0
	v_fmac_f32_e32 v4, v8, v8
	v_fmac_f32_e32 v4, v12, v12
	v_fmac_f32_e32 v4, v32, v32
	v_fmac_f32_e32 v4, v36, v36
	v_fmac_f32_e32 v4, v40, v40
	v_fmac_f32_e32 v4, v44, v44
	s_nop 1
	v_add_f32_dpp v0, v4, v4 quad_perm:[1,0,3,2] row_mask:0xf bank_mask:0xf bound_ctrl:1
	s_nop 1
	v_add_f32_dpp v0, v0, v0 quad_perm:[2,3,0,1] row_mask:0xf bank_mask:0xf bound_ctrl:1
	s_nop 1
	v_add_f32_dpp v0, v0, v0 row_half_mirror row_mask:0xf bank_mask:0xf bound_ctrl:1
	s_nop 1
	v_mov_b32_dpp v4, v0 row_ror:8 row_mask:0xf bank_mask:0xf bound_ctrl:1
	s_and_saveexec_b64 s[6:7], s[4:5]
	v_add_f32_e32 v0, v0, v4
	ds_write_b32 v16, v0 offset:18496
	s_or_b64 exec, exec, s[6:7]
	v_mul_f32_e32 v0, v5, v5
	v_fmac_f32_e32 v0, v1, v1
	v_fmac_f32_e32 v0, v9, v9
	v_fmac_f32_e32 v0, v13, v13
	v_fmac_f32_e32 v0, v33, v33
	v_fmac_f32_e32 v0, v37, v37
	v_fmac_f32_e32 v0, v41, v41
	v_fmac_f32_e32 v0, v45, v45
	s_nop 1
	v_add_f32_dpp v0, v0, v0 quad_perm:[1,0,3,2] row_mask:0xf bank_mask:0xf bound_ctrl:1
	s_nop 1
	v_add_f32_dpp v0, v0, v0 quad_perm:[2,3,0,1] row_mask:0xf bank_mask:0xf bound_ctrl:1
	s_nop 1
	v_add_f32_dpp v0, v0, v0 row_half_mirror row_mask:0xf bank_mask:0xf bound_ctrl:1
	s_nop 1
	v_mov_b32_dpp v1, v0 row_ror:8 row_mask:0xf bank_mask:0xf bound_ctrl:1
	s_and_saveexec_b64 s[6:7], s[4:5]
	v_add_f32_e32 v0, v0, v1
	ds_write_b32 v16, v0 offset:18500
	s_or_b64 exec, exec, s[6:7]
	v_mul_f32_e32 v0, v6, v6
	v_fmac_f32_e32 v0, v2, v2
	v_fmac_f32_e32 v0, v10, v10
	v_fmac_f32_e32 v0, v14, v14
	v_fmac_f32_e32 v0, v34, v34
	v_fmac_f32_e32 v0, v38, v38
	v_fmac_f32_e32 v0, v42, v42
	v_fmac_f32_e32 v0, v46, v46
	s_nop 1
	v_add_f32_dpp v0, v0, v0 quad_perm:[1,0,3,2] row_mask:0xf bank_mask:0xf bound_ctrl:1
	s_nop 1
	v_add_f32_dpp v0, v0, v0 quad_perm:[2,3,0,1] row_mask:0xf bank_mask:0xf bound_ctrl:1
	s_nop 1
	v_add_f32_dpp v0, v0, v0 row_half_mirror row_mask:0xf bank_mask:0xf bound_ctrl:1
	s_nop 1
	v_mov_b32_dpp v1, v0 row_ror:8 row_mask:0xf bank_mask:0xf bound_ctrl:1
	s_and_saveexec_b64 s[6:7], s[4:5]
	v_add_f32_e32 v0, v0, v1
	ds_write_b32 v16, v0 offset:18504
	s_or_b64 exec, exec, s[6:7]
	v_mul_f32_e32 v0, v7, v7
	v_fmac_f32_e32 v0, v3, v3
	v_fmac_f32_e32 v0, v11, v11
	v_fmac_f32_e32 v0, v15, v15
	v_fmac_f32_e32 v0, v35, v35
	v_fmac_f32_e32 v0, v39, v39
	v_fmac_f32_e32 v0, v43, v43
	v_fmac_f32_e32 v0, v47, v47
	s_nop 1
	v_add_f32_dpp v0, v0, v0 quad_perm:[1,0,3,2] row_mask:0xf bank_mask:0xf bound_ctrl:1
	s_nop 1
	v_add_f32_dpp v0, v0, v0 quad_perm:[2,3,0,1] row_mask:0xf bank_mask:0xf bound_ctrl:1
	s_nop 1
	v_add_f32_dpp v0, v0, v0 row_half_mirror row_mask:0xf bank_mask:0xf bound_ctrl:1
	s_nop 1
	v_mov_b32_dpp v1, v0 row_ror:8 row_mask:0xf bank_mask:0xf bound_ctrl:1
	s_and_saveexec_b64 s[6:7], s[4:5]
	v_add_f32_e32 v0, v0, v1
	ds_write_b32 v16, v0 offset:18508
	s_or_b64 exec, exec, s[6:7]
	v_or_b32_e32 v0, s69, v182
	v_ashrrev_i32_e32 v1, 31, v0
	s_waitcnt lgkmcnt(0)
	s_barrier
; __device__ void phase_attn(const Params& p, char* smem) {
;     ...
;     __syncthreads();
; #pragma unroll
;     for (int m = 0; m < 2; ++m)
; #pragma unroll
;       for (int j = 0; j < 4; ++j) {
;         const int row = m * 16 + lq * 4 + j;
;         const float tot = sSsq[row] + sSsq[32 + row] + sSsq[64 + row] + sSsq[96 + row];
;         const float rr = rsqrtf(tot * (1.f / 512.f) + EPS);
; #pragma unroll
;         for (int hh = 0; hh < 2; ++hh)
; #pragma unroll
;           for (int nn = 0; nn < 4; ++nn)
;             mixed[(size_t)(tok0 + row) * 1024 + (w * 2 + hh) * 64 + nn * 16 + l15] =
;                 f2bf((hh == 0 ? sO[((m * 4 + nn) * 4 + j) * 64 + lane] : O1[m][nn][j]) * rr);
;       }
	v_lshrrev_b32_e32 v216, 6, v197
	v_mul_u32_u24_e32 v217, 0x1200, v216
	v_bfe_u32 v218, v197, 4, 2
	v_mul_u32_u24_e32 v218, 0x240, v218
	v_and_b32_e32 v219, 15, v197
	v_lshl_add_u32 v218, v219, 1, v218
	v_add_u32_e32 v216, v217, v218
	v_lshlrev_b64 v[30:31], 11, v[0:1]
	ds_read_b128 v[14:17], v130 offset:18432
	ds_read_b128 v[18:21], v130 offset:18560
	ds_read_b128 v[22:25], v130 offset:18688
	ds_read_b128 v[26:29], v130 offset:18816
	ds_read_b128 v[0:3], v130 offset:18496
	ds_read_b128 v[4:7], v130 offset:18624
	s_waitcnt lgkmcnt(4)
	v_pk_add_f32 v[12:13], v[14:15], v[18:19]
	ds_read_b128 v[8:11], v130 offset:18752
	s_waitcnt lgkmcnt(4)
	v_pk_add_f32 v[18:19], v[12:13], v[22:23]
	ds_read_b128 v[12:15], v130 offset:18880
	s_waitcnt lgkmcnt(4)
	v_pk_add_f32 v[22:23], v[18:19], v[26:27]
	v_mov_b64_e32 v[18:19], s[40:41]
	v_pk_fma_f32 v[22:23], v[22:23], s[38:39], v[18:19] op_sel_hi:[1,0,0]
	v_pk_add_f32 v[16:17], v[16:17], v[20:21]
	v_mul_f32_e32 v26, 0x4b800000, v22
	v_cmp_gt_f32_e32 vcc, s47, v22
	v_pk_add_f32 v[16:17], v[16:17], v[24:25]
	s_waitcnt lgkmcnt(2)
	v_pk_add_f32 v[0:1], v[0:1], v[4:5]
	v_cndmask_b32_e32 v22, v22, v26, vcc
	v_rsq_f32_e32 v22, v22
	v_lshl_add_u64 v[26:27], v[144:145], 0, v[30:31]
	ds_read2st64_b32 v[30:31], v184 offset0:80 offset1:81
	ds_read2st64_b32 v[64:65], v184 offset0:88 offset1:89
	v_pk_add_f32 v[16:17], v[16:17], v[28:29]
	v_mul_f32_e32 v66, 0x45800000, v22
	v_cndmask_b32_e32 v22, v22, v66, vcc
	ds_read2st64_b32 v[66:67], v184 offset0:84 offset1:85
	ds_read2st64_b32 v[68:69], v184 offset0:86 offset1:87
	ds_read2st64_b32 v[70:71], v184 offset0:82 offset1:83
	s_waitcnt lgkmcnt(4)
	v_mul_f32_e32 v30, v30, v22
	v_bfe_u32 v72, v30, 16, 1
	v_add3_u32 v30, v30, v72, s52
	ds_write_b16_d16_hi v216, v30 offset:0
	s_waitcnt lgkmcnt(2)
	v_mul_f32_e32 v30, v66, v22
	v_bfe_u32 v66, v30, 16, 1
	v_add3_u32 v30, v30, v66, s52
	ds_write_b16_d16_hi v216, v30 offset:32
	ds_read2st64_b32 v[72:73], v184 offset0:92 offset1:93
	ds_read2st64_b32 v[74:75], v184 offset0:94 offset1:95
	ds_read2st64_b32 v[76:77], v184 offset0:90 offset1:91
	v_mul_f32_e32 v30, v64, v22
	v_bfe_u32 v64, v30, 16, 1
	v_add3_u32 v30, v30, v64, s52
	ds_write_b16_d16_hi v216, v30 offset:64
	s_waitcnt lgkmcnt(2)
	v_mul_f32_e32 v30, v72, v22
	v_bfe_u32 v64, v30, 16, 1
	v_add3_u32 v30, v30, v64, s52
	ds_write_b16_d16_hi v216, v30 offset:96
	v_mul_f32_e32 v30, v48, v22
	v_bfe_u32 v48, v30, 16, 1
	v_add3_u32 v30, v30, v48, s52
	ds_write_b16_d16_hi v216, v30 offset:53248
	v_mul_f32_e32 v30, v52, v22
	v_bfe_u32 v48, v30, 16, 1
	v_add3_u32 v30, v30, v48, s52
	ds_write_b16_d16_hi v216, v30 offset:53280
	v_mul_f32_e32 v30, v56, v22
	v_bfe_u32 v48, v30, 16, 1
	v_add3_u32 v30, v30, v48, s52
	ds_write_b16_d16_hi v216, v30 offset:53312
	v_mul_f32_e32 v30, 0x4b800000, v23
	v_cmp_gt_f32_e32 vcc, s47, v23
	v_mul_f32_e32 v22, v60, v22
	v_pk_fma_f32 v[16:17], v[16:17], s[38:39], v[18:19] op_sel_hi:[1,0,0]
	v_cndmask_b32_e32 v23, v23, v30, vcc
	v_rsq_f32_e32 v23, v23
	v_bfe_u32 v30, v22, 16, 1
	v_add3_u32 v22, v22, v30, s52
	ds_write_b16_d16_hi v216, v22 offset:53344
	v_mul_f32_e32 v22, 0x45800000, v23
	v_cndmask_b32_e32 v26, v23, v22, vcc
	v_or_b32_e32 v22, s69, v187
	v_ashrrev_i32_e32 v23, 31, v22
	v_mul_f32_e32 v27, v31, v26
	v_lshlrev_b64 v[22:23], 11, v[22:23]
	v_bfe_u32 v30, v27, 16, 1
	v_lshl_add_u64 v[22:23], v[144:145], 0, v[22:23]
	v_add3_u32 v27, v27, v30, s52
	ds_write_b16_d16_hi v216, v27 offset:144
	v_mul_f32_e32 v27, v67, v26
	v_bfe_u32 v30, v27, 16, 1
	v_add3_u32 v27, v27, v30, s52
	ds_write_b16_d16_hi v216, v27 offset:176
	v_mul_f32_e32 v27, v65, v26
	v_bfe_u32 v30, v27, 16, 1
	v_add3_u32 v27, v27, v30, s52
	ds_write_b16_d16_hi v216, v27 offset:208
	v_mul_f32_e32 v27, v73, v26
	v_bfe_u32 v30, v27, 16, 1
	v_add3_u32 v27, v27, v30, s52
	ds_write_b16_d16_hi v216, v27 offset:240
	v_mul_f32_e32 v27, v49, v26
	v_bfe_u32 v30, v27, 16, 1
	v_add3_u32 v27, v27, v30, s52
	ds_write_b16_d16_hi v216, v27 offset:53392
	v_mul_f32_e32 v27, v53, v26
	v_bfe_u32 v30, v27, 16, 1
	v_add3_u32 v27, v27, v30, s52
	ds_write_b16_d16_hi v216, v27 offset:53424
	v_mul_f32_e32 v27, v57, v26
	v_bfe_u32 v30, v27, 16, 1
	v_mul_f32_e32 v20, 0x4b800000, v16
	v_cmp_gt_f32_e32 vcc, s47, v16
	v_add3_u32 v27, v27, v30, s52
	v_mul_f32_e32 v26, v61, v26
	v_cndmask_b32_e32 v16, v16, v20, vcc
	ds_write_b16_d16_hi v216, v27 offset:53456
	v_bfe_u32 v27, v26, 16, 1
	v_rsq_f32_e32 v16, v16
	v_add3_u32 v26, v26, v27, s52
	ds_write_b16_d16_hi v216, v26 offset:53488
	v_or_b32_e32 v22, s69, v188
	v_ashrrev_i32_e32 v23, 31, v22
	v_lshlrev_b64 v[20:21], 11, v[22:23]
	v_mul_f32_e32 v22, 0x45800000, v16
	v_cndmask_b32_e32 v16, v16, v22, vcc
	v_mul_f32_e32 v22, v70, v16
	v_bfe_u32 v23, v22, 16, 1
	v_lshl_add_u64 v[20:21], v[144:145], 0, v[20:21]
	v_add3_u32 v22, v22, v23, s52
	ds_write_b16_d16_hi v216, v22 offset:288
	v_mul_f32_e32 v22, v68, v16
	v_bfe_u32 v23, v22, 16, 1
	v_add3_u32 v22, v22, v23, s52
	ds_write_b16_d16_hi v216, v22 offset:320
	s_waitcnt lgkmcnt(0)
; __device__ void phase_attn(const Params& p, char* smem) {
;     ...
; #pragma unroll
;     for (int m = 0; m < 2; ++m)
; #pragma unroll
;       for (int j = 0; j < 4; ++j) {
;         const int row = m * 16 + lq * 4 + j;
;         const float tot = sSsq[row] + sSsq[32 + row] + sSsq[64 + row] + sSsq[96 + row];
;         const float rr = rsqrtf(tot * (1.f / 512.f) + EPS);
; #pragma unroll
;         for (int hh = 0; hh < 2; ++hh)
; #pragma unroll
;           for (int nn = 0; nn < 4; ++nn)
;             mixed[(size_t)(tok0 + row) * 1024 + (w * 2 + hh) * 64 + nn * 16 + l15] =
;                 f2bf((hh == 0 ? sO[((m * 4 + nn) * 4 + j) * 64 + lane] : O1[m][nn][j]) * rr);
;       }
	v_mul_f32_e32 v22, v76, v16
	v_bfe_u32 v23, v22, 16, 1
	v_add3_u32 v22, v22, v23, s52
	ds_write_b16_d16_hi v216, v22 offset:352
	v_mul_f32_e32 v22, v74, v16
	v_bfe_u32 v23, v22, 16, 1
	v_add3_u32 v22, v22, v23, s52
	ds_write_b16_d16_hi v216, v22 offset:384
	v_mul_f32_e32 v22, v50, v16
	v_bfe_u32 v23, v22, 16, 1
	v_add3_u32 v22, v22, v23, s52
	ds_write_b16_d16_hi v216, v22 offset:53536
	v_mul_f32_e32 v22, v54, v16
	v_bfe_u32 v23, v22, 16, 1
	v_add3_u32 v22, v22, v23, s52
	ds_write_b16_d16_hi v216, v22 offset:53568
	v_mul_f32_e32 v22, v58, v16
	v_bfe_u32 v23, v22, 16, 1
	v_add3_u32 v22, v22, v23, s52
	ds_write_b16_d16_hi v216, v22 offset:53600
	v_mul_f32_e32 v22, 0x4b800000, v17
	v_cmp_gt_f32_e32 vcc, s47, v17
	v_mul_f32_e32 v16, v62, v16
	v_pk_add_f32 v[0:1], v[0:1], v[8:9]
	v_cndmask_b32_e32 v17, v17, v22, vcc
	v_rsq_f32_e32 v17, v17
	v_bfe_u32 v22, v16, 16, 1
	v_add3_u32 v16, v16, v22, s52
	ds_write_b16_d16_hi v216, v16 offset:53632
	v_mul_f32_e32 v16, 0x45800000, v17
	v_cndmask_b32_e32 v20, v17, v16, vcc
	v_or_b32_e32 v16, s69, v189
	v_ashrrev_i32_e32 v17, 31, v16
	v_mul_f32_e32 v21, v71, v20
	v_lshlrev_b64 v[16:17], 11, v[16:17]
	v_bfe_u32 v22, v21, 16, 1
	v_lshl_add_u64 v[16:17], v[144:145], 0, v[16:17]
	v_add3_u32 v21, v21, v22, s52
	ds_write_b16_d16_hi v216, v21 offset:432
	v_mul_f32_e32 v21, v69, v20
	v_bfe_u32 v22, v21, 16, 1
	v_add3_u32 v21, v21, v22, s52
	ds_write_b16_d16_hi v216, v21 offset:464
	v_mul_f32_e32 v21, v77, v20
	v_bfe_u32 v22, v21, 16, 1
	v_add3_u32 v21, v21, v22, s52
	ds_write_b16_d16_hi v216, v21 offset:496
	v_mul_f32_e32 v21, v75, v20
	v_bfe_u32 v22, v21, 16, 1
	v_add3_u32 v21, v21, v22, s52
	ds_write_b16_d16_hi v216, v21 offset:528
	v_mul_f32_e32 v21, v51, v20
	v_bfe_u32 v22, v21, 16, 1
	v_add3_u32 v21, v21, v22, s52
	ds_write_b16_d16_hi v216, v21 offset:53680
	v_mul_f32_e32 v21, v55, v20
	v_bfe_u32 v22, v21, 16, 1
	v_add3_u32 v21, v21, v22, s52
	ds_write_b16_d16_hi v216, v21 offset:53712
	v_mul_f32_e32 v21, v59, v20
	v_pk_add_f32 v[0:1], v[0:1], v[12:13]
	v_bfe_u32 v22, v21, 16, 1
	v_pk_fma_f32 v[0:1], v[0:1], s[38:39], v[18:19] op_sel_hi:[1,0,0]
	v_add3_u32 v21, v21, v22, s52
	v_mul_f32_e32 v20, v63, v20
	v_mul_f32_e32 v4, 0x4b800000, v0
	v_cmp_gt_f32_e32 vcc, s47, v0
	ds_write_b16_d16_hi v216, v21 offset:53744
	v_bfe_u32 v21, v20, 16, 1
	v_cndmask_b32_e32 v0, v0, v4, vcc
	v_add3_u32 v20, v20, v21, s52
	v_rsq_f32_e32 v0, v0
	ds_write_b16_d16_hi v216, v20 offset:53776
	v_or_b32_e32 v16, s69, v190
	v_ashrrev_i32_e32 v17, 31, v16
	ds_read2st64_b32 v[8:9], v184 offset0:96 offset1:97
	ds_read2st64_b32 v[12:13], v184 offset0:104 offset1:105
	v_lshlrev_b64 v[16:17], 11, v[16:17]
	v_lshl_add_u64 v[4:5], v[144:145], 0, v[16:17]
	v_mul_f32_e32 v16, 0x45800000, v0
	v_cndmask_b32_e32 v0, v0, v16, vcc
	ds_read2st64_b32 v[16:17], v184 offset0:100 offset1:101
	ds_read2st64_b32 v[20:21], v184 offset0:102 offset1:103
	ds_read2st64_b32 v[22:23], v184 offset0:98 offset1:99
	s_waitcnt lgkmcnt(4)
	v_mul_f32_e32 v8, v8, v0
	v_bfe_u32 v24, v8, 16, 1
	v_add3_u32 v8, v8, v24, s52
	ds_write_b16_d16_hi v216, v8 offset:2304
	s_waitcnt lgkmcnt(2)
	v_mul_f32_e32 v8, v16, v0
	v_bfe_u32 v16, v8, 16, 1
	v_add3_u32 v8, v8, v16, s52
	ds_write_b16_d16_hi v216, v8 offset:2336
	ds_read2st64_b32 v[24:25], v184 offset0:108 offset1:109
	ds_read2st64_b32 v[26:27], v184 offset0:110 offset1:111
	ds_read2st64_b32 v[28:29], v184 offset0:106 offset1:107
	v_mul_f32_e32 v8, v12, v0
	v_bfe_u32 v12, v8, 16, 1
	v_add3_u32 v8, v8, v12, s52
	ds_write_b16_d16_hi v216, v8 offset:2368
	s_waitcnt lgkmcnt(2)
	v_mul_f32_e32 v8, v24, v0
	v_bfe_u32 v12, v8, 16, 1
	v_add3_u32 v8, v8, v12, s52
	ds_write_b16_d16_hi v216, v8 offset:2400
	v_mul_f32_e32 v8, v32, v0
	v_bfe_u32 v12, v8, 16, 1
	v_add3_u32 v8, v8, v12, s52
	ds_write_b16_d16_hi v216, v8 offset:55552
	v_mul_f32_e32 v8, v36, v0
	v_bfe_u32 v12, v8, 16, 1
	v_add3_u32 v8, v8, v12, s52
	ds_write_b16_d16_hi v216, v8 offset:55584
	v_mul_f32_e32 v8, v40, v0
	v_bfe_u32 v12, v8, 16, 1
	v_add3_u32 v8, v8, v12, s52
	ds_write_b16_d16_hi v216, v8 offset:55616
	v_mul_f32_e32 v8, 0x4b800000, v1
	v_cmp_gt_f32_e32 vcc, s47, v1
	v_mul_f32_e32 v0, v44, v0
	v_pk_add_f32 v[2:3], v[2:3], v[6:7]
	v_cndmask_b32_e32 v1, v1, v8, vcc
	v_rsq_f32_e32 v1, v1
	v_bfe_u32 v8, v0, 16, 1
	v_add3_u32 v0, v0, v8, s52
	ds_write_b16_d16_hi v216, v0 offset:55648
	v_mul_f32_e32 v0, 0x45800000, v1
	v_cndmask_b32_e32 v4, v1, v0, vcc
	v_or_b32_e32 v0, s69, v191
	v_ashrrev_i32_e32 v1, 31, v0
	v_mul_f32_e32 v5, v9, v4
	v_lshlrev_b64 v[0:1], 11, v[0:1]
	v_bfe_u32 v8, v5, 16, 1
	v_lshl_add_u64 v[0:1], v[144:145], 0, v[0:1]
	v_add3_u32 v5, v5, v8, s52
	ds_write_b16_d16_hi v216, v5 offset:2448
	v_mul_f32_e32 v5, v17, v4
	v_bfe_u32 v8, v5, 16, 1
	v_add3_u32 v5, v5, v8, s52
	ds_write_b16_d16_hi v216, v5 offset:2480
	v_mul_f32_e32 v5, v13, v4
	v_bfe_u32 v8, v5, 16, 1
	v_add3_u32 v5, v5, v8, s52
	ds_write_b16_d16_hi v216, v5 offset:2512
	v_mul_f32_e32 v5, v25, v4
	v_bfe_u32 v8, v5, 16, 1
	v_add3_u32 v5, v5, v8, s52
	ds_write_b16_d16_hi v216, v5 offset:2544
	v_mul_f32_e32 v5, v33, v4
	v_bfe_u32 v8, v5, 16, 1
	v_add3_u32 v5, v5, v8, s52
	ds_write_b16_d16_hi v216, v5 offset:55696
	v_mul_f32_e32 v5, v37, v4
	v_bfe_u32 v8, v5, 16, 1
	v_add3_u32 v5, v5, v8, s52
	ds_write_b16_d16_hi v216, v5 offset:55728
	v_mul_f32_e32 v5, v41, v4
	v_bfe_u32 v8, v5, 16, 1
	v_add3_u32 v5, v5, v8, s52
	v_mul_f32_e32 v4, v45, v4
	v_pk_add_f32 v[2:3], v[2:3], v[10:11]
	ds_write_b16_d16_hi v216, v5 offset:55760
	v_bfe_u32 v5, v4, 16, 1
	v_pk_add_f32 v[2:3], v[2:3], v[14:15]
	v_add3_u32 v4, v4, v5, s52
	v_pk_fma_f32 v[2:3], v[2:3], s[38:39], v[18:19] op_sel_hi:[1,0,0]
	ds_write_b16_d16_hi v216, v4 offset:55792
	v_mul_f32_e32 v1, 0x4b800000, v2
	v_cmp_gt_f32_e32 vcc, s47, v2
	v_or_b32_e32 v0, s69, v194
	v_and_b32_e32 v24, 64, v199
	v_cndmask_b32_e32 v1, v2, v1, vcc
	v_rsq_f32_e32 v2, v1
	v_ashrrev_i32_e32 v1, 31, v0
	v_lshlrev_b64 v[0:1], 11, v[0:1]
	v_lshl_add_u64 v[0:1], v[144:145], 0, v[0:1]
	v_mul_f32_e32 v4, 0x45800000, v2
	v_cndmask_b32_e32 v2, v2, v4, vcc
	v_mul_f32_e32 v4, v22, v2
	v_bfe_u32 v5, v4, 16, 1
	v_add3_u32 v4, v4, v5, s52
	ds_write_b16_d16_hi v216, v4 offset:2592
	v_mul_f32_e32 v4, v20, v2
	v_bfe_u32 v5, v4, 16, 1
	v_add3_u32 v4, v4, v5, s52
	ds_write_b16_d16_hi v216, v4 offset:2624
	s_waitcnt lgkmcnt(0)
; __device__ __forceinline__ float bflo(unsigned w) { return __uint_as_float(w << 16); }
; __device__ __forceinline__ float bfhi(unsigned w) { return __uint_as_float(w & 0xFFFF0000u); }
; __device__ void phase_attn(const Params& p, char* smem) {
;     ...
;         for (int hh = 0; hh < 2; ++hh)
; #pragma unroll
;           for (int nn = 0; nn < 4; ++nn)
;             mixed[(size_t)(tok0 + row) * 1024 + (w * 2 + hh) * 64 + nn * 16 + l15] =
;                 f2bf((hh == 0 ? sO[((m * 4 + nn) * 4 + j) * 64 + lane] : O1[m][nn][j]) * rr);
;       }
;     ...
;       const int c8 = lane * 8;
;       float w0[8], w1[8], w2[8];
; #pragma unroll
;       for (int i = 0; i < 8; ++i) {
;         w0[i] = p.conv_w[c8 + i]; w1[i] = p.conv_w[512 + c8 + i]; w2[i] = p.conv_w[1024 + c8 + i];
;       }
;       for (int i = 0; i < 8; ++i) {
;         const int pos = q0 + w * 8 + i;
;         const size_t tg = (size_t)(b * S + pos);
;         float pr[3][8];
; #pragma unroll
;         for (int d = 0; d < 3; ++d) {
;           const int pp = pos - 2 + d;
;           if (pp >= 0) {
;             const uint4 cc = *(const uint4*)(bcx + (tg - 2 + d) * 1536 + 512 + c8);
;             const uint4 xx = *(const uint4*)(bcx + (tg - 2 + d) * 1536 + 1024 + c8);
;             pr[d][0] = bflo(cc.x) * bflo(xx.x); pr[d][1] = bfhi(cc.x) * bfhi(xx.x);
;             pr[d][2] = bflo(cc.y) * bflo(xx.y); pr[d][3] = bfhi(cc.y) * bfhi(xx.y);
;             pr[d][4] = bflo(cc.z) * bflo(xx.z); pr[d][5] = bfhi(cc.z) * bfhi(xx.z);
;             pr[d][6] = bflo(cc.w) * bflo(xx.w); pr[d][7] = bfhi(cc.w) * bfhi(xx.w);
;           } else {
; #pragma unroll
;             for (int e = 0; e < 8; ++e) pr[d][e] = 0.f;
;           }
;         }
;         const uint4 bb = *(const uint4*)(bcx + tg * 1536 + c8);
	v_mul_f32_e32 v4, v28, v2
	v_bfe_u32 v5, v4, 16, 1
	v_add3_u32 v4, v4, v5, s52
	ds_write_b16_d16_hi v216, v4 offset:2656
	v_mul_f32_e32 v4, v26, v2
	v_bfe_u32 v5, v4, 16, 1
	v_add3_u32 v4, v4, v5, s52
	ds_write_b16_d16_hi v216, v4 offset:2688
	v_mul_f32_e32 v4, v34, v2
	v_bfe_u32 v5, v4, 16, 1
	v_add3_u32 v4, v4, v5, s52
	ds_write_b16_d16_hi v216, v4 offset:55840
	v_mul_f32_e32 v4, v38, v2
	v_bfe_u32 v5, v4, 16, 1
	v_add3_u32 v4, v4, v5, s52
	ds_write_b16_d16_hi v216, v4 offset:55872
	v_mul_f32_e32 v4, v42, v2
	v_bfe_u32 v5, v4, 16, 1
	v_add3_u32 v4, v4, v5, s52
	ds_write_b16_d16_hi v216, v4 offset:55904
	v_mul_f32_e32 v4, 0x4b800000, v3
	v_cmp_gt_f32_e32 vcc, s47, v3
	v_mul_f32_e32 v2, v46, v2
	v_add_u32_e32 v24, 64, v24
	v_cndmask_b32_e32 v3, v3, v4, vcc
	v_rsq_f32_e32 v3, v3
	v_bfe_u32 v4, v2, 16, 1
	v_add3_u32 v2, v2, v4, s52
	ds_write_b16_d16_hi v216, v2 offset:55936
	v_mul_f32_e32 v0, 0x45800000, v3
	v_cndmask_b32_e32 v2, v3, v0, vcc
	v_or_b32_e32 v0, s69, v195
	v_ashrrev_i32_e32 v1, 31, v0
	v_mul_f32_e32 v3, v23, v2
	v_lshlrev_b64 v[0:1], 11, v[0:1]
	v_bfe_u32 v4, v3, 16, 1
	v_lshl_add_u64 v[0:1], v[144:145], 0, v[0:1]
	v_add3_u32 v3, v3, v4, s52
	ds_write_b16_d16_hi v216, v3 offset:2736
	v_mul_f32_e32 v3, v21, v2
	v_bfe_u32 v4, v3, 16, 1
	v_add3_u32 v3, v3, v4, s52
	ds_write_b16_d16_hi v216, v3 offset:2768
	v_mul_f32_e32 v3, v29, v2
	v_bfe_u32 v4, v3, 16, 1
	v_add3_u32 v3, v3, v4, s52
	ds_write_b16_d16_hi v216, v3 offset:2800
	v_mul_f32_e32 v3, v27, v2
	v_bfe_u32 v4, v3, 16, 1
	v_add3_u32 v3, v3, v4, s52
	ds_write_b16_d16_hi v216, v3 offset:2832
	v_mul_f32_e32 v3, v35, v2
	v_bfe_u32 v4, v3, 16, 1
	v_add3_u32 v3, v3, v4, s52
	ds_write_b16_d16_hi v216, v3 offset:55984
	v_mul_f32_e32 v3, v39, v2
	v_bfe_u32 v4, v3, 16, 1
	v_add3_u32 v3, v3, v4, s52
	ds_write_b16_d16_hi v216, v3 offset:56016
	v_mul_f32_e32 v3, v43, v2
	v_bfe_u32 v4, v3, 16, 1
	v_add3_u32 v3, v3, v4, s52
	v_mul_f32_e32 v2, v47, v2
	ds_write_b16_d16_hi v216, v3 offset:56048
	v_bfe_u32 v3, v2, 16, 1
	v_add3_u32 v2, v2, v3, s52
	ds_write_b16_d16_hi v216, v2 offset:56080
	v_and_b32_e32 v218, 63, v197
	v_lshrrev_b32_e32 v219, 3, v218
	v_and_b32_e32 v218, 7, v218
	v_mul_u32_u24_e32 v220, 0x90, v219
	v_lshl_add_u32 v220, v218, 4, v220
	v_add_u32_e32 v220, v217, v220
	v_lshrrev_b32_e32 v221, 6, v197
	v_lshlrev_b32_e32 v221, 8, v221
	v_lshl_add_u32 v221, v219, 11, v221
	v_lshl_add_u32 v221, v218, 4, v221
	s_lshl_b32 s96, s69, 11
	s_add_u32 s96, s60, s96
	s_addc_u32 s97, s61, 0
	s_add_u32 s96, s96, 0x67a0000
	s_addc_u32 s97, s97, 0
	s_waitcnt lgkmcnt(0)
	ds_read_b128 v[224:227], v220 offset:0
	ds_read_b128 v[228:231], v220 offset:53248
	ds_read_b128 v[232:235], v220 offset:1152
	ds_read_b128 v[236:239], v220 offset:54400
	ds_read_b128 v[240:243], v220 offset:2304
	ds_read_b128 v[244:247], v220 offset:55552
	ds_read_b128 v[248:251], v220 offset:3456
	ds_read_b128 v[252:255], v220 offset:56704
	s_waitcnt lgkmcnt(7)
	global_store_dwordx4 v221, v[224:227], s[96:97]
	s_waitcnt lgkmcnt(6)
	global_store_dwordx4 v221, v[228:231], s[96:97] offset:128
	s_add_u32 s96, s96, 0x4000
	s_addc_u32 s97, s97, 0
	s_waitcnt lgkmcnt(5)
	global_store_dwordx4 v221, v[232:235], s[96:97]
	s_waitcnt lgkmcnt(4)
	global_store_dwordx4 v221, v[236:239], s[96:97] offset:128
	s_add_u32 s96, s96, 0x4000
	s_addc_u32 s97, s97, 0
	s_waitcnt lgkmcnt(3)
	global_store_dwordx4 v221, v[240:243], s[96:97]
	s_waitcnt lgkmcnt(2)
	global_store_dwordx4 v221, v[244:247], s[96:97] offset:128
	s_add_u32 s96, s96, 0x4000
	s_addc_u32 s97, s97, 0
	s_waitcnt lgkmcnt(1)
	global_store_dwordx4 v221, v[248:251], s[96:97]
	s_waitcnt lgkmcnt(0)
	global_store_dwordx4 v221, v[252:255], s[96:97] offset:128
	s_nop 0
	global_load_dwordx4 v[216:219], v[138:139], off
	global_load_dwordx4 v[220:223], v[138:139], off offset:16
	global_load_dwordx4 v[224:227], v[138:139], off offset:2048
	global_load_dwordx4 v[228:231], v[138:139], off offset:2064
	global_load_dwordx4 v[232:235], v[140:141], off
	global_load_dwordx4 v[236:239], v[140:141], off offset:16
	v_readfirstlane_b32 s8, v185
	s_nop 3
	s_add_u32 s8, s8, s68
	s_add_u32 s100, s8, s67
	s_add_i32 s6, s100, -2
	s_mul_i32 s6, s6, 0xc00
	s_ashr_i32 s7, s6, 31
	s_add_u32 s96, s60, s6
	s_addc_u32 s97, s61, s7
	s_add_u32 s96, s96, 0xb7a0000
	s_addc_u32 s97, s97, 0
	s_lshl_b32 s6, s100, 11
	s_add_u32 s98, s60, s6
	s_addc_u32 s99, s61, 0
	s_add_u32 s98, s98, 0x67a0000
	s_addc_u32 s99, s99, 0
	global_load_dwordx4 v[0:3], v146, s[96:97] offset:1024
	global_load_dwordx4 v[4:7], v146, s[96:97] offset:2048
	s_add_u32 s96, s96, 0xc00
	s_addc_u32 s97, s97, 0
	global_load_dwordx4 v[8:11], v146, s[96:97] offset:1024
	global_load_dwordx4 v[12:15], v146, s[96:97] offset:2048
	s_add_u32 s96, s96, 0xc00
	s_addc_u32 s97, s97, 0
	global_load_dwordx4 v[16:19], v146, s[96:97] offset:1024
	global_load_dwordx4 v[20:23], v146, s[96:97] offset:2048
	global_load_dwordx4 v[80:83], v146, s[96:97]
	s_add_u32 s96, s96, 0xc00
	s_addc_u32 s97, s97, 0
	global_load_dwordx4 v[24:27], v146, s[96:97] offset:1024
	global_load_dwordx4 v[28:31], v146, s[96:97] offset:2048
	global_load_dwordx4 v[84:87], v146, s[96:97]
	s_add_u32 s96, s96, 0xc00
	s_addc_u32 s97, s97, 0
	global_load_dwordx4 v[32:35], v146, s[96:97] offset:1024
	global_load_dwordx4 v[36:39], v146, s[96:97] offset:2048
	global_load_dwordx4 v[88:91], v146, s[96:97]
	s_add_u32 s96, s96, 0xc00
	s_addc_u32 s97, s97, 0
	global_load_dwordx4 v[40:43], v146, s[96:97] offset:1024
	global_load_dwordx4 v[44:47], v146, s[96:97] offset:2048
	global_load_dwordx4 v[92:95], v146, s[96:97]
	s_add_u32 s96, s96, 0xc00
	s_addc_u32 s97, s97, 0
	global_load_dwordx4 v[48:51], v146, s[96:97] offset:1024
	global_load_dwordx4 v[52:55], v146, s[96:97] offset:2048
	global_load_dwordx4 v[96:99], v146, s[96:97]
	s_add_u32 s96, s96, 0xc00
	s_addc_u32 s97, s97, 0
	global_load_dwordx4 v[56:59], v146, s[96:97] offset:1024
	global_load_dwordx4 v[60:63], v146, s[96:97] offset:2048
	global_load_dwordx4 v[100:103], v146, s[96:97]
	s_add_u32 s96, s96, 0xc00
	s_addc_u32 s97, s97, 0
	global_load_dwordx4 v[64:67], v146, s[96:97] offset:1024
	global_load_dwordx4 v[68:71], v146, s[96:97] offset:2048
	global_load_dwordx4 v[104:107], v146, s[96:97]
	s_add_u32 s96, s96, 0xc00
	s_addc_u32 s97, s97, 0
	global_load_dwordx4 v[72:75], v146, s[96:97] offset:1024
	global_load_dwordx4 v[76:79], v146, s[96:97] offset:2048
	global_load_dwordx4 v[108:111], v146, s[96:97]
	s_waitcnt vmcnt(0)
	s_cmp_lg_u32 s8, 0
	s_cbranch_scc1 .Lconv_nz
	v_mov_b32_e32 v0, 0
	v_mov_b32_e32 v1, 0
	v_mov_b32_e32 v2, 0
	v_mov_b32_e32 v3, 0
	v_mov_b32_e32 v4, 0
	v_mov_b32_e32 v5, 0
	v_mov_b32_e32 v6, 0
	v_mov_b32_e32 v7, 0
	v_mov_b32_e32 v8, 0
	v_mov_b32_e32 v9, 0
	v_mov_b32_e32 v10, 0
	v_mov_b32_e32 v11, 0
	v_mov_b32_e32 v12, 0
	v_mov_b32_e32 v13, 0
	v_mov_b32_e32 v14, 0
	v_mov_b32_e32 v15, 0
